# v38 stacked plus shortened wave-uniform predicate tests in the attention dispatch (s_andn2 instead of v_cndmask+v_cmp)
# speedup vs baseline: 1.0069x; 1.0049x over previous
; #define AF_WAITV(n) asm volatile("s_waitcnt vmcnt(" #n ")" ::: "memory")
; #define AF_BAR() do { __builtin_amdgcn_s_barrier(); asm volatile("" ::: "memory"); } while (0)
; __device__ __forceinline__ void attn_fast(const Ptrs& P, LAS unsigned char* lds, int G, int bid) {
;     ...
;                 for (int i = 0; i < nt; ++i) {
;                     const int j = j_lo + i;
;                     if (i + 2 < nt) AF_WAITV(8); else if (i + 1 < nt) AF_WAITV(4); else AF_WAITV(0);
;                     AF_BAR();
;                     if (i + 3 < nt) AF_ISSUE((i + 3) & 3, KB, VB, DINP, 64 * (j + 3), true);
;                     int hi[2], lo[2]; bool act[2];
;                     const bool needmask = (j == qb) || (br == 2 && 64 * j <= 64 * qb + 63 - 512);
; #pragma unroll
;                     for (int ct = 0; ct < 2; ++ct) {
;                         if (br == 1) { const unsigned wd = SELM[(8 * w + 4 * ct + qi) * 4 + (j >> 5)]; const bool bit = (wd >> (j & 31)) & 1u;
;                             act[ct] = __ballot(bit) != 0ull; hi[ct] = bit ? tq[ct] : -1; lo[ct] = NEGBIG; }
;                         else { act[ct] = true; hi[ct] = tq[ct]; lo[ct] = tq[ct] - 512; }
.LBB0_590:
	s_add_i32 s6, s67, s3
	s_ashr_i32 s7, s6, 5
	s_lshl_b32 s7, s7, 2
	s_add_i32 s7, s7, 0
	s_add_i32 s61, s7, 0x20400
	s_lshl_b32 s60, 1, s6
	s_mov_b64 s[8:9], -1
	s_andn2_b64 s[6:7], exec, s[54:55]
	s_andn2_b64 vcc, exec, s[54:55]
	v_add_u32_e32 v102, s61, v186
	v_mov_b32_e32 v219, v208
	v_mov_b32_e32 v220, v212
	s_mov_b64 s[62:63], -1
	s_cbranch_vccnz .LBB0_592
	s_and_b32 s61, s3, 31
	s_cmp_lg_u32 s61, 0
	s_cbranch_scc1 .Lselm_have
	ds_read_b32 v248, v102
	ds_read_b32 v249, v102 offset:64
	s_waitcnt lgkmcnt(0)

; #define LAS __attribute__((address_space(3)))
; template <bool a0, bool a1> __device__ __forceinline__ void af_qk(const LAS unsigned char* kbuf, const unsigned (&kl)[4], const half8 (&qf)[2][4], f32x4 (&s)[2][4]) {
;     const LAS unsigned char* ka[4];
;     { int _ln; asm volatile("v_mov_b32 %0, %1" : "=v"(_ln) : "v"(kl[0]));
;       const int fr_ = _ln & 15, e_ = (_ln >> 4) ^ fr_;
; #pragma unroll
;       for (int ks = 0; ks < 4; ++ks) ka[ks] = kbuf + fr_ * 256 + ((e_ ^ (4 * ks)) << 4); }
;     half8 kf[2][4];
; #pragma unroll
;     for (int ks = 0; ks < 4; ++ks) kf[0][ks] = *(const LAS half8*)(ka[ks]);
; #pragma unroll
;     for (int kt = 0; kt < 4; ++kt) {
;         if (kt < 3) {
; #pragma unroll
;             for (int ks = 0; ks < 4; ++ks) kf[(kt + 1) & 1][ks] = *(const LAS half8*)(ka[ks] + (kt + 1) * 4096); }
;         s[0][kt] = (f32x4){0.f, 0.f, 0.f, 0.f}; s[1][kt] = (f32x4){0.f, 0.f, 0.f, 0.f};
; #pragma unroll
;         for (int ks = 0; ks < 4; ++ks) {
;             if (a0) s[0][kt] = __builtin_amdgcn_mfma_f32_16x16x32_f16(kf[kt & 1][ks], qf[0][ks], s[0][kt], 0, 0, 0);
;             if (a1) s[1][kt] = __builtin_amdgcn_mfma_f32_16x16x32_f16(kf[kt & 1][ks], qf[1][ks], s[1][kt], 0, 0, 0); }
;         __builtin_amdgcn_sched_barrier(0);
;     }
; }
; __device__ __forceinline__ void af_maskraw(f32x4 (&s)[4], int mbase, int mstep, int fq, int hi, int lo) {
; #pragma unroll
;     for (int kt = 0; kt < 4; ++kt)
; #pragma unroll
;         for (int jj = 0; jj < 4; ++jj) { const int met = mbase + mstep * (16 * kt + 4 * fq + jj); s[kt][jj] = (met <= hi && met > lo) ? s[kt][jj] : -3.0e38f; }
; }
.LBB0_610:
	s_andn2_b64 vcc, exec, s[6:7]
	s_cbranch_vccnz .LBB0_619
	v_mov_b32 v102, v172
	s_nop 0
	v_and_b32_e32 v103, 15, v102
	v_lshl_add_u32 v126, v103, 8, s64
	v_lshlrev_b32_e32 v103, 4, v103
	v_bitop3_b32 v127, v103, v102, -16 bitop3:0x78
	v_add_u32_e32 v102, v126, v127
	v_xad_u32 v103, v127, 64, v126
	v_xad_u32 v104, v127, s77, v126
	v_xad_u32 v105, v127, s78, v126
	ds_read_b128 v[134:137], v102
	ds_read_b128 v[138:141], v103
	ds_read_b128 v[142:145], v104
	ds_read_b128 v[146:149], v105
	ds_read_b128 v[150:153], v102 offset:4096
	ds_read_b128 v[154:157], v103 offset:4096
	ds_read_b128 v[158:161], v104 offset:4096
	ds_read_b128 v[162:165], v105 offset:4096
	s_waitcnt lgkmcnt(4)
	v_mfma_f32_16x16x32_f16 v[130:133], v[134:137], v[6:9], 0
	v_mfma_f32_16x16x32_f16 v[114:117], v[134:137], v[22:25], 0
	v_mfma_f32_16x16x32_f16 v[130:133], v[138:141], v[10:13], v[130:133]
	v_mfma_f32_16x16x32_f16 v[114:117], v[138:141], v[26:29], v[114:117]
	v_mfma_f32_16x16x32_f16 v[130:133], v[142:145], v[14:17], v[130:133]
	v_mfma_f32_16x16x32_f16 v[114:117], v[142:145], v[30:33], v[114:117]
	v_mfma_f32_16x16x32_f16 v[130:133], v[146:149], v[18:21], v[130:133]
	v_mfma_f32_16x16x32_f16 v[114:117], v[146:149], v[34:37], v[114:117]
	ds_read_b128 v[134:137], v102 offset:8192
	ds_read_b128 v[138:141], v103 offset:8192
	ds_read_b128 v[142:145], v104 offset:8192
	ds_read_b128 v[146:149], v105 offset:8192
	s_waitcnt lgkmcnt(4)
	v_mfma_f32_16x16x32_f16 v[126:129], v[150:153], v[6:9], 0
	v_mfma_f32_16x16x32_f16 v[110:113], v[150:153], v[22:25], 0
	v_mfma_f32_16x16x32_f16 v[126:129], v[154:157], v[10:13], v[126:129]
	v_mfma_f32_16x16x32_f16 v[110:113], v[154:157], v[26:29], v[110:113]
	v_mfma_f32_16x16x32_f16 v[126:129], v[158:161], v[14:17], v[126:129]
	v_mfma_f32_16x16x32_f16 v[110:113], v[158:161], v[30:33], v[110:113]
	v_mfma_f32_16x16x32_f16 v[126:129], v[162:165], v[18:21], v[126:129]
	v_mfma_f32_16x16x32_f16 v[110:113], v[162:165], v[34:37], v[110:113]
	ds_read_b128 v[150:153], v102 offset:12288
	ds_read_b128 v[154:157], v103 offset:12288
	ds_read_b128 v[158:161], v104 offset:12288
	ds_read_b128 v[162:165], v105 offset:12288
	s_waitcnt lgkmcnt(4)
	v_mfma_f32_16x16x32_f16 v[122:125], v[134:137], v[6:9], 0
	v_mfma_f32_16x16x32_f16 v[106:109], v[134:137], v[22:25], 0
	v_mfma_f32_16x16x32_f16 v[122:125], v[138:141], v[10:13], v[122:125]
	v_mfma_f32_16x16x32_f16 v[106:109], v[138:141], v[26:29], v[106:109]
	v_mfma_f32_16x16x32_f16 v[122:125], v[142:145], v[14:17], v[122:125]
	v_mfma_f32_16x16x32_f16 v[106:109], v[142:145], v[30:33], v[106:109]
	v_mfma_f32_16x16x32_f16 v[122:125], v[146:149], v[18:21], v[122:125]
	v_mfma_f32_16x16x32_f16 v[106:109], v[146:149], v[34:37], v[106:109]
	s_waitcnt lgkmcnt(0)
	v_mfma_f32_16x16x32_f16 v[118:121], v[150:153], v[6:9], 0
	v_mfma_f32_16x16x32_f16 v[102:105], v[150:153], v[22:25], 0
	v_mfma_f32_16x16x32_f16 v[118:121], v[154:157], v[10:13], v[118:121]
	v_mfma_f32_16x16x32_f16 v[102:105], v[154:157], v[26:29], v[102:105]
	v_mfma_f32_16x16x32_f16 v[118:121], v[158:161], v[14:17], v[118:121]
	v_mfma_f32_16x16x32_f16 v[102:105], v[158:161], v[30:33], v[102:105]
	v_mfma_f32_16x16x32_f16 v[118:121], v[162:165], v[18:21], v[118:121]
	v_mfma_f32_16x16x32_f16 v[102:105], v[162:165], v[34:37], v[102:105]
	s_nop 5
	s_andn2_b64 s[8:9], exec, s[60:61]
	s_andn2_b64 vcc, exec, s[60:61]
	s_cbranch_vccnz .LBB0_613
	v_add_u32_e32 v148, s16, v173
	v_add_u32_e32 v147, 2, v148
	v_add_u32_e32 v146, 3, v148
	v_add_u32_e32 v145, 16, v148
	v_add_u32_e32 v144, 17, v148
	v_add_u32_e32 v143, 18, v148
	v_add_u32_e32 v142, 19, v148
	v_add_u32_e32 v141, 32, v148
	v_add_u32_e32 v140, 33, v148
	v_add_u32_e32 v139, 34, v148
	v_add_u32_e32 v138, 35, v148
	v_add_u32_e32 v137, 48, v148
	v_add_u32_e32 v136, 49, v148
	v_add_u32_e32 v135, 50, v148
	v_add_u32_e32 v134, 51, v148
	v_cmp_le_i32_e32 vcc, v148, v219
	v_cmp_gt_i32_e64 s[6:7], v148, v220
	s_and_b64 vcc, vcc, s[6:7]
	v_cndmask_b32_e32 v130, v202, v130, vcc
	v_cmp_lt_i32_e32 vcc, v148, v219
	v_cmp_ge_i32_e64 s[6:7], v148, v220
	s_and_b64 vcc, vcc, s[6:7]
	v_cndmask_b32_e32 v131, v202, v131, vcc
	v_cmp_le_i32_e32 vcc, v147, v219
	v_cmp_gt_i32_e64 s[6:7], v147, v220
	s_and_b64 vcc, vcc, s[6:7]
	v_cndmask_b32_e32 v132, v202, v132, vcc
	v_cmp_le_i32_e32 vcc, v146, v219
	v_cmp_gt_i32_e64 s[6:7], v146, v220
	s_and_b64 vcc, vcc, s[6:7]
	v_cndmask_b32_e32 v133, v202, v133, vcc
	v_cmp_le_i32_e32 vcc, v145, v219
	v_cmp_gt_i32_e64 s[6:7], v145, v220
	s_and_b64 vcc, vcc, s[6:7]
	v_cndmask_b32_e32 v126, v202, v126, vcc
	v_cmp_le_i32_e32 vcc, v144, v219
	v_cmp_gt_i32_e64 s[6:7], v144, v220
	s_and_b64 vcc, vcc, s[6:7]
	v_cndmask_b32_e32 v127, v202, v127, vcc
	v_cmp_le_i32_e32 vcc, v143, v219
	v_cmp_gt_i32_e64 s[6:7], v143, v220
	s_and_b64 vcc, vcc, s[6:7]
	v_cndmask_b32_e32 v128, v202, v128, vcc
	v_cmp_le_i32_e32 vcc, v142, v219
	v_cmp_gt_i32_e64 s[6:7], v142, v220
	s_and_b64 vcc, vcc, s[6:7]
	v_cndmask_b32_e32 v129, v202, v129, vcc
	v_cmp_le_i32_e32 vcc, v141, v219
	v_cmp_gt_i32_e64 s[6:7], v141, v220
	s_and_b64 vcc, vcc, s[6:7]
	v_cndmask_b32_e32 v122, v202, v122, vcc
	v_cmp_le_i32_e32 vcc, v140, v219
	v_cmp_gt_i32_e64 s[6:7], v140, v220
	s_and_b64 vcc, vcc, s[6:7]
	v_cndmask_b32_e32 v123, v202, v123, vcc
	v_cmp_le_i32_e32 vcc, v139, v219
	v_cmp_gt_i32_e64 s[6:7], v139, v220
	s_and_b64 vcc, vcc, s[6:7]
	v_cndmask_b32_e32 v124, v202, v124, vcc
	v_cmp_le_i32_e32 vcc, v138, v219
	v_cmp_gt_i32_e64 s[6:7], v138, v220
	s_and_b64 vcc, vcc, s[6:7]
	v_cndmask_b32_e32 v125, v202, v125, vcc
	v_cmp_le_i32_e32 vcc, v137, v219
	v_cmp_gt_i32_e64 s[6:7], v137, v220
	s_and_b64 vcc, vcc, s[6:7]
	v_cndmask_b32_e32 v118, v202, v118, vcc
	v_cmp_le_i32_e32 vcc, v136, v219
	v_cmp_gt_i32_e64 s[6:7], v136, v220
	s_and_b64 vcc, vcc, s[6:7]
	v_cndmask_b32_e32 v119, v202, v119, vcc
	v_cmp_le_i32_e32 vcc, v135, v219
	v_cmp_gt_i32_e64 s[6:7], v135, v220
	s_and_b64 vcc, vcc, s[6:7]
	v_cndmask_b32_e32 v120, v202, v120, vcc
	v_cmp_le_i32_e32 vcc, v134, v219
	v_cmp_gt_i32_e64 s[6:7], v134, v220
	s_and_b64 vcc, vcc, s[6:7]
	v_cndmask_b32_e32 v121, v202, v121, vcc

; #define AF_WAITV(n) asm volatile("s_waitcnt vmcnt(" #n ")" ::: "memory")
; #define AF_BAR() do { __builtin_amdgcn_s_barrier(); asm volatile("" ::: "memory"); } while (0)
; __device__ __forceinline__ void attn_fast(const Ptrs& P, LAS unsigned char* lds, int G, int bid) {
;     ...
;                 for (int i = 0; i < nt; ++i) {
;                     const int j = j_lo + i;
;                     if (i + 2 < nt) AF_WAITV(8); else if (i + 1 < nt) AF_WAITV(4); else AF_WAITV(0);
;                     AF_BAR();
;                     if (i + 3 < nt) AF_ISSUE((i + 3) & 3, KB, VB, DINP, 64 * (j + 3), true);
;                     int hi[2], lo[2]; bool act[2];
;                     const bool needmask = (j == qb) || (br == 2 && 64 * j <= 64 * qb + 63 - 512);
; #pragma unroll
;                     for (int ct = 0; ct < 2; ++ct) {
;                         if (br == 1) { const unsigned wd = SELM[(8 * w + 4 * ct + qi) * 4 + (j >> 5)]; const bool bit = (wd >> (j & 31)) & 1u;
;                             act[ct] = __ballot(bit) != 0ull; hi[ct] = bit ? tq[ct] : -1; lo[ct] = NEGBIG; }
;                         else { act[ct] = true; hi[ct] = tq[ct]; lo[ct] = tq[ct] - 512; }
.Lu2_583:
.Lu2_590:
	s_add_i32 s6, s67, s3
	s_ashr_i32 s7, s6, 5
	s_lshl_b32 s7, s7, 2
	s_add_i32 s7, s7, 0
	s_add_i32 s61, s7, 0x20400
	s_lshl_b32 s60, 1, s6
	s_mov_b64 s[8:9], -1
	s_andn2_b64 s[6:7], exec, s[54:55]
	s_andn2_b64 vcc, exec, s[54:55]
	v_add_u32_e32 v94, s61, v186
	v_mov_b32_e32 v219, v208
	v_mov_b32_e32 v220, v212
	s_mov_b64 s[62:63], -1
	s_cbranch_vccnz .Lu2_592
	s_and_b32 s61, s3, 31
	s_cmp_lg_u32 s61, 0
	s_cbranch_scc1 .Lu2_have
	ds_read_b32 v248, v94
	ds_read_b32 v249, v94 offset:64
	s_waitcnt lgkmcnt(0)

; #define LAS __attribute__((address_space(3)))
; template <bool a0, bool a1> __device__ __forceinline__ void af_qk(const LAS unsigned char* kbuf, const unsigned (&kl)[4], const half8 (&qf)[2][4], f32x4 (&s)[2][4]) {
;     const LAS unsigned char* ka[4];
;     { int _ln; asm volatile("v_mov_b32 %0, %1" : "=v"(_ln) : "v"(kl[0]));
;       const int fr_ = _ln & 15, e_ = (_ln >> 4) ^ fr_;
; #pragma unroll
;       for (int ks = 0; ks < 4; ++ks) ka[ks] = kbuf + fr_ * 256 + ((e_ ^ (4 * ks)) << 4); }
;     half8 kf[2][4];
; #pragma unroll
;     for (int ks = 0; ks < 4; ++ks) kf[0][ks] = *(const LAS half8*)(ka[ks]);
; #pragma unroll
;     for (int kt = 0; kt < 4; ++kt) {
;         if (kt < 3) {
; #pragma unroll
;             for (int ks = 0; ks < 4; ++ks) kf[(kt + 1) & 1][ks] = *(const LAS half8*)(ka[ks] + (kt + 1) * 4096); }
;         s[0][kt] = (f32x4){0.f, 0.f, 0.f, 0.f}; s[1][kt] = (f32x4){0.f, 0.f, 0.f, 0.f};
; #pragma unroll
;         for (int ks = 0; ks < 4; ++ks) {
;             if (a0) s[0][kt] = __builtin_amdgcn_mfma_f32_16x16x32_f16(kf[kt & 1][ks], qf[0][ks], s[0][kt], 0, 0, 0);
;             if (a1) s[1][kt] = __builtin_amdgcn_mfma_f32_16x16x32_f16(kf[kt & 1][ks], qf[1][ks], s[1][kt], 0, 0, 0); }
;         __builtin_amdgcn_sched_barrier(0);
;     }
; }
; __device__ __forceinline__ void af_maskraw(f32x4 (&s)[4], int mbase, int mstep, int fq, int hi, int lo) {
; #pragma unroll
;     for (int kt = 0; kt < 4; ++kt)
; #pragma unroll
;         for (int jj = 0; jj < 4; ++jj) { const int met = mbase + mstep * (16 * kt + 4 * fq + jj); s[kt][jj] = (met <= hi && met > lo) ? s[kt][jj] : -3.0e38f; }
; }
.Lu2_610:
	s_andn2_b64 vcc, exec, s[6:7]
	s_cbranch_vccnz .Lu2_619
	v_mov_b32 v94, v172
	s_nop 0
	v_and_b32_e32 v95, 15, v94
	v_lshl_add_u32 v50, v95, 8, s64
	v_lshlrev_b32_e32 v95, 4, v95
	v_bitop3_b32 v51, v95, v94, -16 bitop3:0x78
	v_add_u32_e32 v94, v50, v51
	v_xad_u32 v95, v51, 64, v50
	v_xad_u32 v96, v51, s77, v50
	v_xad_u32 v97, v51, s78, v50
	ds_read_b128 v[98:101], v94
	ds_read_b128 v[90:93], v95
	ds_read_b128 v[78:81], v96
	ds_read_b128 v[70:73], v97
	ds_read_b128 v[58:61], v94 offset:4096
	ds_read_b128 v[54:57], v95 offset:4096
	ds_read_b128 v[42:45], v96 offset:4096
	ds_read_b128 v[38:41], v97 offset:4096
	s_waitcnt lgkmcnt(4)
	v_mfma_f32_16x16x32_f16 v[46:49], v[98:101], v[6:9], 0
	v_mfma_f32_16x16x32_f16 v[74:77], v[98:101], v[22:25], 0
	v_mfma_f32_16x16x32_f16 v[46:49], v[90:93], v[10:13], v[46:49]
	v_mfma_f32_16x16x32_f16 v[74:77], v[90:93], v[26:29], v[74:77]
	v_mfma_f32_16x16x32_f16 v[46:49], v[78:81], v[14:17], v[46:49]
	v_mfma_f32_16x16x32_f16 v[74:77], v[78:81], v[30:33], v[74:77]
	v_mfma_f32_16x16x32_f16 v[46:49], v[70:73], v[18:21], v[46:49]
	v_mfma_f32_16x16x32_f16 v[74:77], v[70:73], v[34:37], v[74:77]
	ds_read_b128 v[98:101], v94 offset:8192
	ds_read_b128 v[90:93], v95 offset:8192
	ds_read_b128 v[78:81], v96 offset:8192
	ds_read_b128 v[70:73], v97 offset:8192
	s_waitcnt lgkmcnt(4)
	v_mfma_f32_16x16x32_f16 v[50:53], v[58:61], v[6:9], 0
	v_mfma_f32_16x16x32_f16 v[82:85], v[58:61], v[22:25], 0
	v_mfma_f32_16x16x32_f16 v[50:53], v[54:57], v[10:13], v[50:53]
	v_mfma_f32_16x16x32_f16 v[82:85], v[54:57], v[26:29], v[82:85]
	v_mfma_f32_16x16x32_f16 v[50:53], v[42:45], v[14:17], v[50:53]
	v_mfma_f32_16x16x32_f16 v[82:85], v[42:45], v[30:33], v[82:85]
	v_mfma_f32_16x16x32_f16 v[50:53], v[38:41], v[18:21], v[50:53]
	v_mfma_f32_16x16x32_f16 v[82:85], v[38:41], v[34:37], v[82:85]
	ds_read_b128 v[58:61], v94 offset:12288
	ds_read_b128 v[54:57], v95 offset:12288
	ds_read_b128 v[42:45], v96 offset:12288
	ds_read_b128 v[38:41], v97 offset:12288
	s_waitcnt lgkmcnt(4)
	v_mfma_f32_16x16x32_f16 v[62:65], v[98:101], v[6:9], 0
	v_mfma_f32_16x16x32_f16 v[86:89], v[98:101], v[22:25], 0
	v_mfma_f32_16x16x32_f16 v[62:65], v[90:93], v[10:13], v[62:65]
	v_mfma_f32_16x16x32_f16 v[86:89], v[90:93], v[26:29], v[86:89]
	v_mfma_f32_16x16x32_f16 v[62:65], v[78:81], v[14:17], v[62:65]
	v_mfma_f32_16x16x32_f16 v[86:89], v[78:81], v[30:33], v[86:89]
	v_mfma_f32_16x16x32_f16 v[62:65], v[70:73], v[18:21], v[62:65]
	v_mfma_f32_16x16x32_f16 v[86:89], v[70:73], v[34:37], v[86:89]
	s_waitcnt lgkmcnt(0)
	v_mfma_f32_16x16x32_f16 v[66:69], v[58:61], v[6:9], 0
	v_mfma_f32_16x16x32_f16 v[94:97], v[58:61], v[22:25], 0
	v_mfma_f32_16x16x32_f16 v[66:69], v[54:57], v[10:13], v[66:69]
	v_mfma_f32_16x16x32_f16 v[94:97], v[54:57], v[26:29], v[94:97]
	v_mfma_f32_16x16x32_f16 v[66:69], v[42:45], v[14:17], v[66:69]
	v_mfma_f32_16x16x32_f16 v[94:97], v[42:45], v[30:33], v[94:97]
	v_mfma_f32_16x16x32_f16 v[66:69], v[38:41], v[18:21], v[66:69]
	v_mfma_f32_16x16x32_f16 v[94:97], v[38:41], v[34:37], v[94:97]
	s_nop 5
	s_andn2_b64 s[8:9], exec, s[60:61]
	s_andn2_b64 vcc, exec, s[60:61]
	s_cbranch_vccnz .Lu2_613
	v_add_u32_e32 v72, s16, v173
	v_add_u32_e32 v71, 2, v72
	v_add_u32_e32 v70, 3, v72
	v_add_u32_e32 v81, 16, v72
	v_add_u32_e32 v80, 17, v72
	v_add_u32_e32 v79, 18, v72
	v_add_u32_e32 v78, 19, v72
	v_add_u32_e32 v93, 32, v72
	v_add_u32_e32 v92, 33, v72
	v_add_u32_e32 v91, 34, v72
	v_add_u32_e32 v90, 35, v72
	v_add_u32_e32 v101, 48, v72
	v_add_u32_e32 v100, 49, v72
	v_add_u32_e32 v99, 50, v72
	v_add_u32_e32 v98, 51, v72
	v_cmp_le_i32_e32 vcc, v72, v219
	v_cmp_gt_i32_e64 s[6:7], v72, v220
	s_and_b64 vcc, vcc, s[6:7]
	v_cndmask_b32_e32 v46, v202, v46, vcc
	v_cmp_lt_i32_e32 vcc, v72, v219
	v_cmp_ge_i32_e64 s[6:7], v72, v220
	s_and_b64 vcc, vcc, s[6:7]
	v_cndmask_b32_e32 v47, v202, v47, vcc
	v_cmp_le_i32_e32 vcc, v71, v219
	v_cmp_gt_i32_e64 s[6:7], v71, v220
	s_and_b64 vcc, vcc, s[6:7]
	v_cndmask_b32_e32 v48, v202, v48, vcc
	v_cmp_le_i32_e32 vcc, v70, v219
	v_cmp_gt_i32_e64 s[6:7], v70, v220
	s_and_b64 vcc, vcc, s[6:7]
	v_cndmask_b32_e32 v49, v202, v49, vcc
	v_cmp_le_i32_e32 vcc, v81, v219
	v_cmp_gt_i32_e64 s[6:7], v81, v220
	s_and_b64 vcc, vcc, s[6:7]
	v_cndmask_b32_e32 v50, v202, v50, vcc
	v_cmp_le_i32_e32 vcc, v80, v219
	v_cmp_gt_i32_e64 s[6:7], v80, v220
	s_and_b64 vcc, vcc, s[6:7]
	v_cndmask_b32_e32 v51, v202, v51, vcc
	v_cmp_le_i32_e32 vcc, v79, v219
	v_cmp_gt_i32_e64 s[6:7], v79, v220
	s_and_b64 vcc, vcc, s[6:7]
	v_cndmask_b32_e32 v52, v202, v52, vcc
	v_cmp_le_i32_e32 vcc, v78, v219
	v_cmp_gt_i32_e64 s[6:7], v78, v220
	s_and_b64 vcc, vcc, s[6:7]
	v_cndmask_b32_e32 v53, v202, v53, vcc
	v_cmp_le_i32_e32 vcc, v93, v219
	v_cmp_gt_i32_e64 s[6:7], v93, v220
	s_and_b64 vcc, vcc, s[6:7]
	v_cndmask_b32_e32 v62, v202, v62, vcc
	v_cmp_le_i32_e32 vcc, v92, v219
	v_cmp_gt_i32_e64 s[6:7], v92, v220
	s_and_b64 vcc, vcc, s[6:7]
	v_cndmask_b32_e32 v63, v202, v63, vcc
	v_cmp_le_i32_e32 vcc, v91, v219
	v_cmp_gt_i32_e64 s[6:7], v91, v220
	s_and_b64 vcc, vcc, s[6:7]
	v_cndmask_b32_e32 v64, v202, v64, vcc
	v_cmp_le_i32_e32 vcc, v90, v219
	v_cmp_gt_i32_e64 s[6:7], v90, v220
	s_and_b64 vcc, vcc, s[6:7]
	v_cndmask_b32_e32 v65, v202, v65, vcc
	v_cmp_le_i32_e32 vcc, v101, v219
	v_cmp_gt_i32_e64 s[6:7], v101, v220
	s_and_b64 vcc, vcc, s[6:7]
	v_cndmask_b32_e32 v66, v202, v66, vcc
	v_cmp_le_i32_e32 vcc, v100, v219
	v_cmp_gt_i32_e64 s[6:7], v100, v220
	s_and_b64 vcc, vcc, s[6:7]
	v_cndmask_b32_e32 v67, v202, v67, vcc
	v_cmp_le_i32_e32 vcc, v99, v219
	v_cmp_gt_i32_e64 s[6:7], v99, v220
	s_and_b64 vcc, vcc, s[6:7]
	v_cndmask_b32_e32 v68, v202, v68, vcc
	v_cmp_le_i32_e32 vcc, v98, v219
	v_cmp_gt_i32_e64 s[6:7], v98, v220
	s_and_b64 vcc, vcc, s[6:7]
	v_cndmask_b32_e32 v69, v202, v69, vcc
